# sample-row 32x32 pieces: K-split MFMA loop keeps two whole iterations (16 loads) in flight instead of 5+3 with two exposed waits; plus B-pair MFMA order and 4-slot attention ring
# speedup vs baseline: 1.0059x; 1.0059x over previous
; #define MFMA(a, b, c) __builtin_amdgcn_mfma_f32_32x32x16_bf16((a), (b), (c), 0, 0, 0)
; DI int crow(int i, int h) { return (i & 3) + 8 * (i >> 2) + 4 * h; }
; DI int opaque_tid() { int t = threadIdx.x; asm volatile("" : "+v"(t)); return t; }
; DI f32x16 zero16() { f32x16 z; for (int i = 0; i < 16; ++i) z[i] = 0.f; return z; }
; DI void small_tile(const bf16_t* A, size_t lda, int a0, const bf16_t* Bt, size_t ldb, int b0, int K, float* ctile, float* red) {
;     const int t = opaque_tid(), w = t >> 6, lane = t & 63, r = lane & 31, hh = lane >> 5;
;     const int kper = K >> 3;
;     const bf16_t* ap = A + (size_t)(a0 + r) * lda + w * kper + 8 * hh;
;     const bf16_t* bp = Bt + (size_t)(b0 + r) * ldb + w * kper + 8 * hh;
;     f32x16 acc = zero16();
; #pragma unroll 4
;     for (int k = 0; k < kper; k += 16) acc = MFMA(*(const bf16x8*)(ap + k), *(const bf16x8*)(bp + k), acc);
; #pragma unroll
;     for (int i = 0; i < 16; ++i) red[w * 1024 + i * 64 + lane] = acc[i];
;     __syncthreads();
; #pragma unroll
;     for (int q = 0; q < 2; ++q) {
;         const int e = t + 512 * q; float s = 0.f;
; #pragma unroll
;         for (int ww = 0; ww < 8; ++ww) s += red[ww * 1024 + e];
;         const int i = e >> 6, ln = e & 63;
;         ctile[crow(i, ln >> 5) * 33 + (ln & 31)] = s;
;     }
;     __syncthreads();
; }
; DI void phase_p4(const Params& P, unsigned char* lds) {
;     ...
;             small_tile(RO, 1024, MPR + 32 * rg, W1, 1024, 32 * cg, 1024, c1, red);
.LBB0_1411:
	global_load_dwordx4 v[224:227], v[24:25], off offset:-64
	global_load_dwordx4 v[228:231], v[22:23], off offset:-64
	global_load_dwordx4 v[232:235], v[24:25], off offset:-32
	global_load_dwordx4 v[236:239], v[22:23], off offset:-32
	global_load_dwordx4 v[240:243], v[24:25], off
	global_load_dwordx4 v[244:247], v[22:23], off
	global_load_dwordx4 v[248:251], v[24:25], off offset:32
	global_load_dwordx4 v[252:255], v[22:23], off offset:32
	v_lshl_add_u64 v[24:25], v[24:25], 0, s[14:15]
	v_lshl_add_u64 v[22:23], v[22:23], 0, s[14:15]
	global_load_dwordx4 v[52:55], v[24:25], off offset:-64
	global_load_dwordx4 v[56:59], v[22:23], off offset:-64
	global_load_dwordx4 v[60:63], v[24:25], off offset:-32
	global_load_dwordx4 v[64:67], v[22:23], off offset:-32
	global_load_dwordx4 v[68:71], v[24:25], off
	global_load_dwordx4 v[72:75], v[22:23], off
	global_load_dwordx4 v[76:79], v[24:25], off offset:32
	global_load_dwordx4 v[80:83], v[22:23], off offset:32
	v_lshl_add_u64 v[24:25], v[24:25], 0, s[14:15]
	v_lshl_add_u64 v[22:23], v[22:23], 0, s[14:15]
	s_waitcnt vmcnt(14)
	v_mfma_f32_32x32x16_bf16 v[2:17], v[224:227], v[228:231], v[2:17]
	s_waitcnt vmcnt(12)
	v_mfma_f32_32x32x16_bf16 v[2:17], v[232:235], v[236:239], v[2:17]
	s_waitcnt vmcnt(10)
	v_mfma_f32_32x32x16_bf16 v[2:17], v[240:243], v[244:247], v[2:17]
	s_waitcnt vmcnt(8)
	v_mfma_f32_32x32x16_bf16 v[2:17], v[248:251], v[252:255], v[2:17]
	s_waitcnt vmcnt(6)
	v_mfma_f32_32x32x16_bf16 v[2:17], v[52:55], v[56:59], v[2:17]
	s_waitcnt vmcnt(4)
	v_mfma_f32_32x32x16_bf16 v[2:17], v[60:63], v[64:67], v[2:17]
	s_waitcnt vmcnt(2)
	v_mfma_f32_32x32x16_bf16 v[2:17], v[68:71], v[72:75], v[2:17]
	s_waitcnt vmcnt(0)
	v_mfma_f32_32x32x16_bf16 v[2:17], v[76:79], v[80:83], v[2:17]
	s_mov_b32 s23, 0x70
	v_and_b32_e32 v20, 63, v27
	v_lshlrev_b32_e32 v22, 12, v29
	v_lshlrev_b32_e32 v20, 2, v20
	v_add3_u32 v20, 0, v22, v20
	s_nop 6
	ds_write2st64_b32 v20, v2, v3 offset1:1
	ds_write2st64_b32 v20, v4, v5 offset0:2 offset1:3
	ds_write2st64_b32 v20, v6, v7 offset0:4 offset1:5
	ds_write2st64_b32 v20, v8, v9 offset0:6 offset1:7
	ds_write2st64_b32 v20, v10, v11 offset0:8 offset1:9
	ds_write2st64_b32 v20, v12, v13 offset0:10 offset1:11
	ds_write2st64_b32 v20, v14, v15 offset0:12 offset1:13
	ds_write2st64_b32 v20, v16, v17 offset0:14 offset1:15
	v_lshl_add_u32 v4, v27, 2, 0
	s_waitcnt lgkmcnt(0)
	s_barrier
	ds_read_b32 v5, v4
	ds_read_b32 v6, v4 offset:4096
	ds_read_b32 v7, v4 offset:8192
	ds_read_b32 v8, v4 offset:12288
	ds_read_b32 v9, v4 offset:16384
	ds_read_b32 v10, v4 offset:20480
	ds_read_b32 v11, v4 offset:24576
	ds_read_b32 v12, v4 offset:28672
	s_waitcnt lgkmcnt(7)
	v_add_f32_e32 v5, 0, v5
	s_waitcnt lgkmcnt(6)
	v_add_f32_e32 v5, v5, v6
	s_waitcnt lgkmcnt(5)
	v_add_f32_e32 v5, v5, v7
	v_lshrrev_b32_e32 v2, 3, v27
	s_waitcnt lgkmcnt(4)
	v_add_f32_e32 v5, v5, v8
	v_lshlrev_b32_e32 v7, 1, v29
	v_and_b32_e32 v3, 4, v2
	s_waitcnt lgkmcnt(3)
	v_add_f32_e32 v5, v5, v9
	v_bfe_u32 v6, v27, 6, 2
	v_and_b32_e32 v7, 0x3ffffff8, v7
	s_waitcnt lgkmcnt(2)
	v_add_f32_e32 v5, v5, v10
	v_or3_b32 v6, v6, v7, v3
	s_waitcnt lgkmcnt(1)
	v_add_f32_e32 v5, v5, v11
	v_mul_lo_u32 v6, v6, s18
	v_lshlrev_b32_e32 v7, 2, v28
	s_waitcnt lgkmcnt(0)
	v_add_f32_e32 v5, v5, v12
	v_add3_u32 v6, 0, v6, v7
	ds_write_b32 v6, v5 offset:32768
	ds_read_b32 v6, v4 offset:2048
	ds_read_b32 v8, v4 offset:6144
	ds_read_b32 v9, v4 offset:10240
	ds_read_b32 v10, v4 offset:14336
	ds_read_b32 v11, v4 offset:18432
	ds_read_b32 v12, v4 offset:22528
	ds_read_b32 v13, v4 offset:26624
	ds_read_b32 v4, v4 offset:30720
	s_waitcnt lgkmcnt(7)
	v_add_f32_e32 v6, 0, v6
	s_waitcnt lgkmcnt(6)
	v_add_f32_e32 v6, v6, v8
	s_waitcnt lgkmcnt(5)
	v_add_f32_e32 v6, v6, v9
	s_waitcnt lgkmcnt(4)
	v_add_f32_e32 v6, v6, v10
	s_waitcnt lgkmcnt(3)
	v_add_f32_e32 v6, v6, v11
	v_add_u32_e32 v5, 0x200, v27
	s_waitcnt lgkmcnt(2)
	v_add_f32_e32 v6, v6, v12
	s_waitcnt lgkmcnt(1)
	v_add_f32_e32 v6, v6, v13
	v_ashrrev_i32_e32 v5, 6, v5
	s_waitcnt lgkmcnt(0)
	v_add_f32_e32 v4, v6, v4
	v_and_b32_e32 v6, 3, v5
	v_lshlrev_b32_e32 v5, 1, v5
	v_and_b32_e32 v5, 0x3ffffff8, v5
	v_or3_b32 v3, v6, v5, v3
	v_mul_lo_u32 v3, v3, s18
	v_add3_u32 v3, 0, v3, v7
	v_mov_b32_e32 v27, v1
	ds_write_b32 v3, v4 offset:32768
	s_waitcnt lgkmcnt(0)
	s_barrier
	v_mov_b32_e32 v2, 0
	v_ashrrev_i32_e32 v29, 6, v27
	v_lshlrev_b32_e32 v4, 7, v29
	v_ashrrev_i32_e32 v5, 31, v4
	v_and_b32_e32 v28, 31, v27
	v_lshrrev_b32_e32 v3, 1, v27
	v_lshlrev_b64 v[4:5], 1, v[4:5]
	v_and_or_b32 v4, v3, 16, v4
	v_lshlrev_b32_e32 v3, 10, v28
	v_add_lshl_u32 v20, s21, v3, 1
	v_lshl_add_u64 v[6:7], v[4:5], 0, v[20:21]
	v_lshl_add_u64 v[22:23], s[10:11], 0, v[6:7]
	v_add_u32_e32 v6, s22, v28
	v_ashrrev_i32_e32 v7, 31, v6
	v_lshlrev_b64 v[6:7], 11, v[6:7]
	v_lshl_add_u64 v[4:5], v[4:5], 0, v[6:7]
	v_lshl_add_u64 v[24:25], s[12:13], 0, v[4:5]
	s_mov_b32 s21, -16
	v_mov_b32_e32 v3, v2
	v_mov_b32_e32 v4, v2
	v_mov_b32_e32 v5, v2
	v_mov_b32_e32 v6, v2
	v_mov_b32_e32 v7, v2
	v_mov_b32_e32 v8, v2
	v_mov_b32_e32 v9, v2
	v_mov_b32_e32 v10, v2
	v_mov_b32_e32 v11, v2
	v_mov_b32_e32 v12, v2
	v_mov_b32_e32 v13, v2
	v_mov_b32_e32 v14, v2
	v_mov_b32_e32 v15, v2
	v_mov_b32_e32 v16, v2
	v_mov_b32_e32 v17, v2
; #define MFMA(a, b, c) __builtin_amdgcn_mfma_f32_32x32x16_bf16((a), (b), (c), 0, 0, 0)
; DI unsigned pk2(float a, float b) { f32x2 v = {a, b}; bf2_t r = __builtin_convertvector(v, bf2_t); return __builtin_bit_cast(unsigned, r); }
; DI float bflo(unsigned u) { return __uint_as_float(u << 16); }
; DI float bfhi(unsigned u) { return __uint_as_float(u & 0xffff0000u); }
; DI int crow(int i, int h) { return (i & 3) + 8 * (i >> 2) + 4 * h; }
; DI int opaque_tid() { int t = threadIdx.x; asm volatile("" : "+v"(t)); return t; }
; DI f32x16 zero16() { f32x16 z; for (int i = 0; i < 16; ++i) z[i] = 0.f; return z; }
; DI void small_tile(const bf16_t* A, size_t lda, int a0, const bf16_t* Bt, size_t ldb, int b0, int K, float* ctile, float* red) {
;     const int t = opaque_tid(), w = t >> 6, lane = t & 63, r = lane & 31, hh = lane >> 5;
;     const int kper = K >> 3;
;     const bf16_t* ap = A + (size_t)(a0 + r) * lda + w * kper + 8 * hh;
;     const bf16_t* bp = Bt + (size_t)(b0 + r) * ldb + w * kper + 8 * hh;
;     f32x16 acc = zero16();
; #pragma unroll 4
;     for (int k = 0; k < kper; k += 16) acc = MFMA(*(const bf16x8*)(ap + k), *(const bf16x8*)(bp + k), acc);
; #pragma unroll
;     for (int i = 0; i < 16; ++i) red[w * 1024 + i * 64 + lane] = acc[i];
;     __syncthreads();
; #pragma unroll
;     for (int q = 0; q < 2; ++q) {
;         const int e = t + 512 * q; float s = 0.f;
; #pragma unroll
;         for (int ww = 0; ww < 8; ++ww) s += red[ww * 1024 + e];
;         const int i = e >> 6, ln = e & 63;
;         ctile[crow(i, ln >> 5) * 33 + (ln & 31)] = s;
;     }
;     __syncthreads();
; }
; DI void phase_p4(const Params& P, unsigned char* lds) {
;     ...
;             const int rl = t >> 4, cl = (t & 15) * 2; const int srow = 32 * rg + rl, col = 32 * cg + cl;
;             const unsigned ua = *(const unsigned*)(GAs + (size_t)srow * 1024 + col), ub = *(const unsigned*)(GBs + (size_t)srow * 1024 + col);
;             const float m0v = bflo(ua) * c1[rl * 33 + cl] + bflo(ub) * c2[rl * 33 + cl];
;             const float m1v = bfhi(ua) * c1[rl * 33 + cl + 1] + bfhi(ub) * c2[rl * 33 + cl + 1];
;             __builtin_nontemporal_store(pk2(m0v, m1v), (unsigned*)(M + (size_t)(MPR + srow) * 1024 + col));
;             __syncthreads();
.LBB0_1413:
	global_load_dwordx4 v[224:227], v[24:25], off offset:-64
	global_load_dwordx4 v[228:231], v[22:23], off offset:-64
	global_load_dwordx4 v[232:235], v[24:25], off offset:-32
	global_load_dwordx4 v[236:239], v[22:23], off offset:-32
	global_load_dwordx4 v[240:243], v[24:25], off
	global_load_dwordx4 v[244:247], v[22:23], off
	global_load_dwordx4 v[248:251], v[24:25], off offset:32
	global_load_dwordx4 v[252:255], v[22:23], off offset:32
	v_lshl_add_u64 v[24:25], v[24:25], 0, s[14:15]
	v_lshl_add_u64 v[22:23], v[22:23], 0, s[14:15]
	global_load_dwordx4 v[52:55], v[24:25], off offset:-64
	global_load_dwordx4 v[56:59], v[22:23], off offset:-64
	global_load_dwordx4 v[60:63], v[24:25], off offset:-32
	global_load_dwordx4 v[64:67], v[22:23], off offset:-32
	global_load_dwordx4 v[68:71], v[24:25], off
	global_load_dwordx4 v[72:75], v[22:23], off
	global_load_dwordx4 v[76:79], v[24:25], off offset:32
	global_load_dwordx4 v[80:83], v[22:23], off offset:32
	v_lshl_add_u64 v[24:25], v[24:25], 0, s[14:15]
	v_lshl_add_u64 v[22:23], v[22:23], 0, s[14:15]
	s_waitcnt vmcnt(14)
	v_mfma_f32_32x32x16_bf16 v[2:17], v[224:227], v[228:231], v[2:17]
	s_waitcnt vmcnt(12)
	v_mfma_f32_32x32x16_bf16 v[2:17], v[232:235], v[236:239], v[2:17]
	s_waitcnt vmcnt(10)
	v_mfma_f32_32x32x16_bf16 v[2:17], v[240:243], v[244:247], v[2:17]
	s_waitcnt vmcnt(8)
	v_mfma_f32_32x32x16_bf16 v[2:17], v[248:251], v[252:255], v[2:17]
	s_waitcnt vmcnt(6)
	v_mfma_f32_32x32x16_bf16 v[2:17], v[52:55], v[56:59], v[2:17]
	s_waitcnt vmcnt(4)
	v_mfma_f32_32x32x16_bf16 v[2:17], v[60:63], v[64:67], v[2:17]
	s_waitcnt vmcnt(2)
	v_mfma_f32_32x32x16_bf16 v[2:17], v[68:71], v[72:75], v[2:17]
	s_waitcnt vmcnt(0)
	v_mfma_f32_32x32x16_bf16 v[2:17], v[76:79], v[80:83], v[2:17]
	s_mov_b32 s21, 0x70
	v_and_b32_e32 v20, 63, v27
	v_lshlrev_b32_e32 v22, 12, v29
	v_lshlrev_b32_e32 v20, 2, v20
	v_add3_u32 v20, 0, v22, v20
	s_nop 6
	ds_write2st64_b32 v20, v2, v3 offset1:1
	ds_write2st64_b32 v20, v4, v5 offset0:2 offset1:3
	ds_write2st64_b32 v20, v6, v7 offset0:4 offset1:5
	ds_write2st64_b32 v20, v8, v9 offset0:6 offset1:7
	ds_write2st64_b32 v20, v10, v11 offset0:8 offset1:9
	ds_write2st64_b32 v20, v12, v13 offset0:10 offset1:11
	ds_write2st64_b32 v20, v14, v15 offset0:12 offset1:13
	ds_write2st64_b32 v20, v16, v17 offset0:14 offset1:15
	v_lshl_add_u32 v3, v27, 2, 0
	s_waitcnt lgkmcnt(0)
	s_barrier
	ds_read_b32 v4, v3
	ds_read_b32 v5, v3 offset:4096
	ds_read_b32 v6, v3 offset:8192
	ds_read_b32 v7, v3 offset:12288
	ds_read_b32 v8, v3 offset:16384
	ds_read_b32 v9, v3 offset:20480
	ds_read_b32 v10, v3 offset:24576
	ds_read_b32 v11, v3 offset:28672
	s_waitcnt lgkmcnt(7)
	v_add_f32_e32 v4, 0, v4
	s_waitcnt lgkmcnt(6)
	v_add_f32_e32 v4, v4, v5
	s_waitcnt lgkmcnt(5)
	v_add_f32_e32 v4, v4, v6
	v_lshrrev_b32_e32 v2, 3, v27
	s_waitcnt lgkmcnt(4)
	v_add_f32_e32 v4, v4, v7
	v_lshlrev_b32_e32 v6, 1, v29
	v_and_b32_e32 v2, 4, v2
	s_waitcnt lgkmcnt(3)
	v_add_f32_e32 v4, v4, v8
	v_bfe_u32 v5, v27, 6, 2
	v_and_b32_e32 v6, 0x3ffffff8, v6
	s_waitcnt lgkmcnt(2)
	v_add_f32_e32 v4, v4, v9
	v_or3_b32 v5, v5, v6, v2
	s_waitcnt lgkmcnt(1)
	v_add_f32_e32 v4, v4, v10
	v_mul_lo_u32 v5, v5, s18
	v_lshlrev_b32_e32 v6, 2, v28
	s_waitcnt lgkmcnt(0)
	v_add_f32_e32 v4, v4, v11
	v_add3_u32 v5, 0, v5, v6
	ds_write_b32 v5, v4 offset:37120
	ds_read_b32 v5, v3 offset:2048
	ds_read_b32 v7, v3 offset:6144
	ds_read_b32 v8, v3 offset:10240
	ds_read_b32 v9, v3 offset:14336
	ds_read_b32 v10, v3 offset:18432
	ds_read_b32 v11, v3 offset:22528
	ds_read_b32 v12, v3 offset:26624
	ds_read_b32 v3, v3 offset:30720
	s_waitcnt lgkmcnt(7)
	v_add_f32_e32 v5, 0, v5
	s_waitcnt lgkmcnt(6)
	v_add_f32_e32 v5, v5, v7
	s_waitcnt lgkmcnt(5)
	v_add_f32_e32 v5, v5, v8
	s_waitcnt lgkmcnt(4)
	v_add_f32_e32 v5, v5, v9
	s_waitcnt lgkmcnt(3)
	v_add_f32_e32 v5, v5, v10
	v_add_u32_e32 v4, 0x200, v27
	s_waitcnt lgkmcnt(2)
	v_add_f32_e32 v5, v5, v11
	s_waitcnt lgkmcnt(1)
	v_add_f32_e32 v5, v5, v12
	v_ashrrev_i32_e32 v4, 6, v4
	s_waitcnt lgkmcnt(0)
	v_add_f32_e32 v3, v5, v3
	v_and_b32_e32 v5, 3, v4
	v_lshlrev_b32_e32 v4, 1, v4
	v_and_b32_e32 v4, 0x3ffffff8, v4
	v_or3_b32 v2, v5, v4, v2
	v_mul_lo_u32 v2, v2, s18
	v_add3_u32 v2, 0, v2, v6
	s_lshl_b32 s21, s19, 5
	ds_write_b32 v2, v3 offset:37120
	v_add_u32_e32 v2, s20, v19
	s_and_b32 s21, s21, 0x3e0
	v_ashrrev_i32_e32 v3, 31, v2
	v_or_b32_e32 v6, s21, v18
	v_lshlrev_b64 v[2:3], 11, v[2:3]
	v_lshl_add_u64 v[4:5], s[2:3], 0, v[2:3]
	v_lshlrev_b32_e32 v20, 1, v6
	v_lshl_add_u64 v[4:5], v[4:5], 0, v[20:21]
	v_lshl_add_u64 v[6:7], s[4:5], 0, v[2:3]
	s_waitcnt lgkmcnt(0)
	s_barrier
	v_lshl_add_u64 v[6:7], v[6:7], 0, v[20:21]
	global_load_dword v9, v[4:5], off
	global_load_dword v11, v[6:7], off
	v_add_u32_e32 v4, 0x8000, v26
	v_add_u32_e32 v6, 0x9100, v26
	ds_read2_b32 v[4:5], v4 offset1:1
	ds_read2_b32 v[6:7], v6 offset1:1
	v_lshl_add_u64 v[2:3], s[0:1], 0, v[2:3]
	v_readlane_b32 s20, v223, 3
	v_lshl_add_u64 v[2:3], v[2:3], 0, v[20:21]
	s_add_i32 s19, s19, s20
	s_add_i32 s16, s16, s17
	v_add_co_u32_e32 v2, vcc, 0x4100000, v2
	s_cmpk_lt_i32 s19, 0x100
	s_nop 0
	v_addc_co_u32_e32 v3, vcc, 0, v3, vcc
	v_readlane_b32 s21, v223, 4
	s_waitcnt vmcnt(1)
	v_lshlrev_b32_e32 v8, 16, v9
	s_waitcnt vmcnt(0)
	v_lshlrev_b32_e32 v10, 16, v11
	v_and_b32_e32 v11, 0xffff0000, v11
	v_and_b32_e32 v9, 0xffff0000, v9
	s_waitcnt lgkmcnt(0)
	v_pk_mul_f32 v[6:7], v[6:7], v[10:11]
	s_nop 0
	v_pk_fma_f32 v[4:5], v[4:5], v[8:9], v[6:7]
	s_nop 0
	v_cvt_pk_bf16_f32 v4, v4, v5
	global_store_dword v[2:3], v4, off nt
	s_barrier
	s_cbranch_scc1 .LBB0_1410

; #define MFMA(a, b, c) __builtin_amdgcn_mfma_f32_32x32x16_bf16((a), (b), (c), 0, 0, 0)
; DI unsigned pk2(float a, float b) { f32x2 v = {a, b}; bf2_t r = __builtin_convertvector(v, bf2_t); return __builtin_bit_cast(unsigned, r); }
; DI int crow(int i, int h) { return (i & 3) + 8 * (i >> 2) + 4 * h; }
; DI int opaque_tid() { int t = threadIdx.x; asm volatile("" : "+v"(t)); return t; }
; DI f32x16 zero16() { f32x16 z; for (int i = 0; i < 16; ++i) z[i] = 0.f; return z; }
; DI void small_tile(const bf16_t* A, size_t lda, int a0, const bf16_t* Bt, size_t ldb, int b0, int K, float* ctile, float* red) {
;     const int t = opaque_tid(), w = t >> 6, lane = t & 63, r = lane & 31, hh = lane >> 5;
;     const int kper = K >> 3;
;     const bf16_t* ap = A + (size_t)(a0 + r) * lda + w * kper + 8 * hh;
;     const bf16_t* bp = Bt + (size_t)(b0 + r) * ldb + w * kper + 8 * hh;
;     f32x16 acc = zero16();
; #pragma unroll 4
;     for (int k = 0; k < kper; k += 16) acc = MFMA(*(const bf16x8*)(ap + k), *(const bf16x8*)(bp + k), acc);
; #pragma unroll
;     for (int i = 0; i < 16; ++i) red[w * 1024 + i * 64 + lane] = acc[i];
;     __syncthreads();
; #pragma unroll
;     for (int q = 0; q < 2; ++q) {
;         const int e = t + 512 * q; float s = 0.f;
; #pragma unroll
;         for (int ww = 0; ww < 8; ++ww) s += red[ww * 1024 + e];
;         const int i = e >> 6, ln = e & 63;
;         ctile[crow(i, ln >> 5) * 33 + (ln & 31)] = s;
;     }
;     __syncthreads();
; }
; DI void phase_p5(const Params& P, unsigned char* lds) {
;     ...
;             const int rl = t >> 4, cl = (t & 15) * 2; const int srow = 32 * rg + rl, col = 32 * cg + cl;
;             const f32x2 xv = *(const f32x2*)(P.x_sample + (size_t)srow * 1024 + col);
;             f32x2 h2; h2.x = xv.x + c1[rl * 33 + cl]; h2.y = xv.y + c1[rl * 33 + cl + 1];
;             __builtin_nontemporal_store(h2, (f32x2*)(P.out + O_YS + (size_t)srow * 1024 + col));
;             const f32x2 g2 = *(const f32x2*)(P.norm2_g + col);
;             __builtin_nontemporal_store(pk2(h2.x * g2.x, h2.y * g2.y), (unsigned*)(A2 + (size_t)(MPR + srow) * 1024 + col));
;             float ss = h2.x * h2.x + h2.y * h2.y;
; #pragma unroll
;             for (int o = 1; o < 16; o <<= 1) ss += __shfl_xor(ss, o);
;             if ((t & 15) == 0) SSQS[srow * 32 + cg] = ss;
.LBB0_1561:
	global_load_dwordx4 v[224:227], v[22:23], off offset:-64
	global_load_dwordx4 v[228:231], v[20:21], off offset:-64
	global_load_dwordx4 v[232:235], v[22:23], off offset:-32
	global_load_dwordx4 v[236:239], v[20:21], off offset:-32
	global_load_dwordx4 v[240:243], v[22:23], off
	global_load_dwordx4 v[244:247], v[20:21], off
	global_load_dwordx4 v[248:251], v[22:23], off offset:32
	global_load_dwordx4 v[252:255], v[20:21], off offset:32
	v_lshl_add_u64 v[22:23], v[22:23], 0, s[12:13]
	v_lshl_add_u64 v[20:21], v[20:21], 0, s[12:13]
	global_load_dwordx4 v[52:55], v[22:23], off offset:-64
	global_load_dwordx4 v[56:59], v[20:21], off offset:-64
	global_load_dwordx4 v[60:63], v[22:23], off offset:-32
	global_load_dwordx4 v[64:67], v[20:21], off offset:-32
	global_load_dwordx4 v[68:71], v[22:23], off
	global_load_dwordx4 v[72:75], v[20:21], off
	global_load_dwordx4 v[76:79], v[22:23], off offset:32
	global_load_dwordx4 v[80:83], v[20:21], off offset:32
	v_lshl_add_u64 v[22:23], v[22:23], 0, s[12:13]
	v_lshl_add_u64 v[20:21], v[20:21], 0, s[12:13]
	s_waitcnt vmcnt(14)
	v_mfma_f32_32x32x16_bf16 v[2:17], v[224:227], v[228:231], v[2:17]
	s_waitcnt vmcnt(12)
	v_mfma_f32_32x32x16_bf16 v[2:17], v[232:235], v[236:239], v[2:17]
	s_waitcnt vmcnt(10)
	v_mfma_f32_32x32x16_bf16 v[2:17], v[240:243], v[244:247], v[2:17]
	s_waitcnt vmcnt(8)
	v_mfma_f32_32x32x16_bf16 v[2:17], v[248:251], v[252:255], v[2:17]
	s_waitcnt vmcnt(6)
	v_mfma_f32_32x32x16_bf16 v[2:17], v[52:55], v[56:59], v[2:17]
	s_waitcnt vmcnt(4)
	v_mfma_f32_32x32x16_bf16 v[2:17], v[60:63], v[64:67], v[2:17]
	s_waitcnt vmcnt(2)
	v_mfma_f32_32x32x16_bf16 v[2:17], v[68:71], v[72:75], v[2:17]
	s_waitcnt vmcnt(0)
	v_mfma_f32_32x32x16_bf16 v[2:17], v[76:79], v[80:83], v[2:17]
	s_mov_b32 s1, 0x70
	v_and_b32_e32 v18, 63, v28
	v_lshlrev_b32_e32 v20, 12, v30
	v_lshlrev_b32_e32 v18, 2, v18
	v_add3_u32 v18, 0, v20, v18
	s_nop 6
	ds_write2st64_b32 v18, v2, v3 offset1:1
	ds_write2st64_b32 v18, v4, v5 offset0:2 offset1:3
	ds_write2st64_b32 v18, v6, v7 offset0:4 offset1:5
	ds_write2st64_b32 v18, v8, v9 offset0:6 offset1:7
	ds_write2st64_b32 v18, v10, v11 offset0:8 offset1:9
	ds_write2st64_b32 v18, v12, v13 offset0:10 offset1:11
	ds_write2st64_b32 v18, v14, v15 offset0:12 offset1:13
	ds_write2st64_b32 v18, v16, v17 offset0:14 offset1:15
	v_lshl_add_u32 v3, v28, 2, 0
	s_waitcnt lgkmcnt(0)
	s_barrier
	ds_read_b32 v4, v3
	ds_read_b32 v5, v3 offset:4096
	ds_read_b32 v6, v3 offset:8192
	ds_read_b32 v7, v3 offset:12288
	ds_read_b32 v8, v3 offset:16384
	ds_read_b32 v9, v3 offset:20480
	ds_read_b32 v10, v3 offset:24576
	ds_read_b32 v11, v3 offset:28672
	s_waitcnt lgkmcnt(7)
	v_add_f32_e32 v4, 0, v4
	s_waitcnt lgkmcnt(6)
	v_add_f32_e32 v4, v4, v5
	s_waitcnt lgkmcnt(5)
	v_add_f32_e32 v4, v4, v6
	v_lshrrev_b32_e32 v2, 3, v28
	s_waitcnt lgkmcnt(4)
	v_add_f32_e32 v4, v4, v7
	v_lshlrev_b32_e32 v6, 1, v30
	v_and_b32_e32 v2, 4, v2
	s_waitcnt lgkmcnt(3)
	v_add_f32_e32 v4, v4, v8
	v_bfe_u32 v5, v28, 6, 2
	v_and_b32_e32 v6, 0x3ffffff8, v6
	s_waitcnt lgkmcnt(2)
	v_add_f32_e32 v4, v4, v9
	v_or3_b32 v5, v5, v6, v2
	s_waitcnt lgkmcnt(1)
	v_add_f32_e32 v4, v4, v10
	v_mul_lo_u32 v5, v5, s14
	v_lshlrev_b32_e32 v6, 2, v29
	s_waitcnt lgkmcnt(0)
	v_add_f32_e32 v4, v4, v11
	v_add3_u32 v5, 0, v5, v6
	ds_write_b32 v5, v4 offset:32768
	ds_read_b32 v5, v3 offset:2048
	ds_read_b32 v7, v3 offset:6144
	ds_read_b32 v8, v3 offset:10240
	ds_read_b32 v9, v3 offset:14336
	ds_read_b32 v10, v3 offset:18432
	ds_read_b32 v11, v3 offset:22528
	ds_read_b32 v12, v3 offset:26624
	ds_read_b32 v3, v3 offset:30720
	s_waitcnt lgkmcnt(7)
	v_add_f32_e32 v5, 0, v5
	s_waitcnt lgkmcnt(6)
	v_add_f32_e32 v5, v5, v7
	s_waitcnt lgkmcnt(5)
	v_add_f32_e32 v5, v5, v8
	s_waitcnt lgkmcnt(4)
	v_add_f32_e32 v5, v5, v9
	s_waitcnt lgkmcnt(3)
	v_add_f32_e32 v5, v5, v10
	v_add_u32_e32 v4, 0x200, v28
	s_waitcnt lgkmcnt(2)
	v_add_f32_e32 v5, v5, v11
	s_waitcnt lgkmcnt(1)
	v_add_f32_e32 v5, v5, v12
	v_ashrrev_i32_e32 v4, 6, v4
	s_waitcnt lgkmcnt(0)
	v_add_f32_e32 v3, v5, v3
	v_and_b32_e32 v5, 3, v4
	v_lshlrev_b32_e32 v4, 1, v4
	v_and_b32_e32 v4, 0x3ffffff8, v4
	v_or3_b32 v2, v5, v4, v2
	v_mul_lo_u32 v2, v2, s14
	v_add3_u32 v2, 0, v2, v6
	ds_write_b32 v2, v3 offset:32768
	v_add_u32_e32 v2, s0, v24
	s_and_b32 s18, s17, 31
	v_ashrrev_i32_e32 v3, 31, v2
	v_readlane_b32 s36, v223, 7
	v_lshl_or_b32 v10, s18, 5, v25
	v_lshlrev_b64 v[4:5], 12, v[2:3]
	v_readlane_b32 s38, v223, 9
	v_readlane_b32 s39, v223, 10
	v_lshlrev_b32_e32 v18, 2, v10
	s_waitcnt lgkmcnt(0)
	v_lshl_add_u64 v[6:7], s[38:39], 0, v[4:5]
	v_lshl_add_u64 v[6:7], v[6:7], 0, v[18:19]
	s_barrier
	global_load_dwordx2 v[6:7], v[6:7], off
	ds_read2_b32 v[8:9], v26 offset1:1
	v_lshl_add_u64 v[4:5], s[6:7], 0, v[4:5]
	v_lshl_add_u64 v[4:5], v[4:5], 0, v[18:19]
	v_xor_b32_e32 v11, 2, v27
	v_xor_b32_e32 v12, 4, v27
	v_xor_b32_e32 v13, 8, v27
	v_readlane_b32 s37, v223, 8
	v_readlane_b32 s40, v223, 11
	v_readlane_b32 s41, v223, 12
	v_readlane_b32 s42, v223, 13
	v_readlane_b32 s43, v223, 14
	v_readlane_b32 s44, v223, 15
	v_readlane_b32 s45, v223, 16
	v_readlane_b32 s46, v223, 17
	v_readlane_b32 s47, v223, 18
	v_readlane_b32 s48, v223, 19
	v_readlane_b32 s49, v223, 20
	v_readlane_b32 s50, v223, 21
	v_readlane_b32 s51, v223, 22
	s_waitcnt vmcnt(0) lgkmcnt(0)
	v_pk_add_f32 v[6:7], v[6:7], v[8:9]
	global_store_dwordx2 v[4:5], v[6:7], off nt
	global_load_dwordx2 v[8:9], v18, s[68:69]
	v_and_b32_e32 v4, 64, v27
	v_xor_b32_e32 v5, 1, v27
	v_add_u32_e32 v14, 64, v4
	v_cmp_lt_i32_e64 s[0:1], v5, v14
	v_lshlrev_b32_e32 v18, 1, v10
	s_nop 0
	v_cndmask_b32_e64 v4, v27, v5, s[0:1]
	v_lshlrev_b32_e32 v15, 2, v4
	v_pk_mul_f32 v[4:5], v[6:7], v[6:7]
	v_cmp_lt_i32_e64 s[0:1], v11, v14
	v_add_f32_e32 v16, v4, v5
	ds_bpermute_b32 v15, v15, v16
	v_lshlrev_b64 v[4:5], 11, v[2:3]
	v_cndmask_b32_e64 v3, v27, v11, s[0:1]
	v_lshlrev_b32_e32 v3, 2, v3
	v_cmp_lt_i32_e64 s[0:1], v12, v14
	s_waitcnt lgkmcnt(0)
	v_add_f32_e32 v11, v16, v15
	ds_bpermute_b32 v3, v3, v11
	v_cndmask_b32_e64 v12, v27, v12, s[0:1]
	v_lshlrev_b32_e32 v12, 2, v12
	v_cmp_lt_i32_e64 s[0:1], v13, v14
	v_lshl_add_u64 v[4:5], s[4:5], 0, v[4:5]
	s_waitcnt lgkmcnt(0)
	v_add_f32_e32 v3, v11, v3
	ds_bpermute_b32 v12, v12, v3
	v_cndmask_b32_e64 v13, v27, v13, s[0:1]
	v_lshlrev_b32_e32 v13, 2, v13
	v_lshl_add_u64 v[10:11], v[4:5], 0, v[18:19]
	s_waitcnt lgkmcnt(0)
	v_add_f32_e32 v3, v3, v12
	ds_bpermute_b32 v4, v13, v3
	s_waitcnt vmcnt(0)
	v_pk_mul_f32 v[6:7], v[6:7], v[8:9]
	s_nop 0
	v_cvt_pk_bf16_f32 v5, v6, v7
	v_add_co_u32_e64 v6, s[0:1], s15, v10
	s_nop 1
	v_addc_co_u32_e64 v7, s[0:1], 0, v11, s[0:1]
	global_store_dword v[6:7], v5, off nt
	s_and_saveexec_b64 s[0:1], vcc
	s_cbranch_execz .LBB0_1559
	v_lshl_or_b32 v6, v2, 5, s18
	v_ashrrev_i32_e32 v7, 31, v6
	v_lshl_add_u64 v[6:7], v[6:7], 2, s[2:3]
	s_waitcnt lgkmcnt(0)
	v_add_f32_e32 v2, v3, v4
	global_store_dword v[6:7], v2, off
	s_branch .LBB0_1559

; #define MFMA(a, b, c) __builtin_amdgcn_mfma_f32_32x32x16_bf16((a), (b), (c), 0, 0, 0)
; DI int crow(int i, int h) { return (i & 3) + 8 * (i >> 2) + 4 * h; }
; DI int opaque_tid() { int t = threadIdx.x; asm volatile("" : "+v"(t)); return t; }
; DI f32x16 zero16() { f32x16 z; for (int i = 0; i < 16; ++i) z[i] = 0.f; return z; }
; DI void small_tile(const bf16_t* A, size_t lda, int a0, const bf16_t* Bt, size_t ldb, int b0, int K, float* ctile, float* red) {
;     const int t = opaque_tid(), w = t >> 6, lane = t & 63, r = lane & 31, hh = lane >> 5;
;     const int kper = K >> 3;
;     const bf16_t* ap = A + (size_t)(a0 + r) * lda + w * kper + 8 * hh;
;     const bf16_t* bp = Bt + (size_t)(b0 + r) * ldb + w * kper + 8 * hh;
;     f32x16 acc = zero16();
; #pragma unroll 4
;     for (int k = 0; k < kper; k += 16) acc = MFMA(*(const bf16x8*)(ap + k), *(const bf16x8*)(bp + k), acc);
; #pragma unroll
;     for (int i = 0; i < 16; ++i) red[w * 1024 + i * 64 + lane] = acc[i];
;     __syncthreads();
; #pragma unroll
;     for (int q = 0; q < 2; ++q) {
;         const int e = t + 512 * q; float s = 0.f;
; #pragma unroll
;         for (int ww = 0; ww < 8; ++ww) s += red[ww * 1024 + e];
;         const int i = e >> 6, ln = e & 63;
;         ctile[crow(i, ln >> 5) * 33 + (ln & 31)] = s;
;     }
;     __syncthreads();
; }
; DI void phase_p6(const Params& P, unsigned char* lds) {
;     ...
;             small_tile(A2, 1024, MPR + 32 * rg, W, 1024, 32 * cg, 1024, c1, red);
.LBB0_1647:
	global_load_dwordx4 v[224:227], v[22:23], off offset:-64
	global_load_dwordx4 v[228:231], v[20:21], off offset:-64
	global_load_dwordx4 v[232:235], v[22:23], off offset:-32
	global_load_dwordx4 v[236:239], v[20:21], off offset:-32
	global_load_dwordx4 v[240:243], v[22:23], off
	global_load_dwordx4 v[244:247], v[20:21], off
	global_load_dwordx4 v[248:251], v[22:23], off offset:32
	global_load_dwordx4 v[252:255], v[20:21], off offset:32
	v_lshl_add_u64 v[22:23], v[22:23], 0, s[8:9]
	v_lshl_add_u64 v[20:21], v[20:21], 0, s[8:9]
	global_load_dwordx4 v[52:55], v[22:23], off offset:-64
	global_load_dwordx4 v[56:59], v[20:21], off offset:-64
	global_load_dwordx4 v[60:63], v[22:23], off offset:-32
	global_load_dwordx4 v[64:67], v[20:21], off offset:-32
	global_load_dwordx4 v[68:71], v[22:23], off
	global_load_dwordx4 v[72:75], v[20:21], off
	global_load_dwordx4 v[76:79], v[22:23], off offset:32
	global_load_dwordx4 v[80:83], v[20:21], off offset:32
	v_lshl_add_u64 v[22:23], v[22:23], 0, s[8:9]
	v_lshl_add_u64 v[20:21], v[20:21], 0, s[8:9]
	s_waitcnt vmcnt(14)
	v_mfma_f32_32x32x16_bf16 v[2:17], v[224:227], v[228:231], v[2:17]
	s_waitcnt vmcnt(12)
	v_mfma_f32_32x32x16_bf16 v[2:17], v[232:235], v[236:239], v[2:17]
	s_waitcnt vmcnt(10)
	v_mfma_f32_32x32x16_bf16 v[2:17], v[240:243], v[244:247], v[2:17]
	s_waitcnt vmcnt(8)
	v_mfma_f32_32x32x16_bf16 v[2:17], v[248:251], v[252:255], v[2:17]
	s_waitcnt vmcnt(6)
	v_mfma_f32_32x32x16_bf16 v[2:17], v[52:55], v[56:59], v[2:17]
	s_waitcnt vmcnt(4)
	v_mfma_f32_32x32x16_bf16 v[2:17], v[60:63], v[64:67], v[2:17]
	s_waitcnt vmcnt(2)
	v_mfma_f32_32x32x16_bf16 v[2:17], v[68:71], v[72:75], v[2:17]
	s_waitcnt vmcnt(0)
	v_mfma_f32_32x32x16_bf16 v[2:17], v[76:79], v[80:83], v[2:17]
	s_mov_b32 s15, 0x70
	v_and_b32_e32 v18, 63, v28
	v_lshlrev_b32_e32 v20, 12, v30
	v_lshlrev_b32_e32 v18, 2, v18
	v_add3_u32 v18, 0, v20, v18
	s_nop 6
	ds_write2st64_b32 v18, v2, v3 offset1:1
	ds_write2st64_b32 v18, v4, v5 offset0:2 offset1:3
	ds_write2st64_b32 v18, v6, v7 offset0:4 offset1:5
	ds_write2st64_b32 v18, v8, v9 offset0:6 offset1:7
	ds_write2st64_b32 v18, v10, v11 offset0:8 offset1:9
	ds_write2st64_b32 v18, v12, v13 offset0:10 offset1:11
	ds_write2st64_b32 v18, v14, v15 offset0:12 offset1:13
	ds_write2st64_b32 v18, v16, v17 offset0:14 offset1:15
	v_lshl_add_u32 v3, v28, 2, 0
	s_waitcnt lgkmcnt(0)
	s_barrier
	ds_read_b32 v4, v3
	ds_read_b32 v5, v3 offset:4096
	ds_read_b32 v6, v3 offset:8192
	ds_read_b32 v7, v3 offset:12288
	ds_read_b32 v8, v3 offset:16384
	ds_read_b32 v9, v3 offset:20480
	ds_read_b32 v10, v3 offset:24576
	ds_read_b32 v11, v3 offset:28672
	s_waitcnt lgkmcnt(7)
	v_add_f32_e32 v4, 0, v4
	s_waitcnt lgkmcnt(6)
	v_add_f32_e32 v4, v4, v5
	s_waitcnt lgkmcnt(5)
	v_add_f32_e32 v4, v4, v6
	v_lshrrev_b32_e32 v2, 3, v28
	s_waitcnt lgkmcnt(4)
	v_add_f32_e32 v4, v4, v7
	v_lshlrev_b32_e32 v6, 1, v30
	v_and_b32_e32 v2, 4, v2
	s_waitcnt lgkmcnt(3)
	v_add_f32_e32 v4, v4, v8
	v_bfe_u32 v5, v28, 6, 2
	v_and_b32_e32 v6, 0x3ffffff8, v6
	s_waitcnt lgkmcnt(2)
	v_add_f32_e32 v4, v4, v9
	v_or3_b32 v5, v5, v6, v2
	s_waitcnt lgkmcnt(1)
	v_add_f32_e32 v4, v4, v10
	v_mul_lo_u32 v5, v5, s10
	v_lshlrev_b32_e32 v6, 2, v29
	s_waitcnt lgkmcnt(0)
	v_add_f32_e32 v4, v4, v11
	v_add3_u32 v5, 0, v5, v6
	ds_write_b32 v5, v4 offset:32768
	ds_read_b32 v5, v3 offset:2048
	ds_read_b32 v7, v3 offset:6144
	ds_read_b32 v8, v3 offset:10240
	ds_read_b32 v9, v3 offset:14336
	ds_read_b32 v10, v3 offset:18432
	ds_read_b32 v11, v3 offset:22528
	ds_read_b32 v12, v3 offset:26624
	ds_read_b32 v3, v3 offset:30720
	s_waitcnt lgkmcnt(7)
	v_add_f32_e32 v5, 0, v5
	s_waitcnt lgkmcnt(6)
	v_add_f32_e32 v5, v5, v7
	s_waitcnt lgkmcnt(5)
	v_add_f32_e32 v5, v5, v8
	s_waitcnt lgkmcnt(4)
	v_add_f32_e32 v5, v5, v9
	s_waitcnt lgkmcnt(3)
	v_add_f32_e32 v5, v5, v10
	v_add_u32_e32 v4, 0x200, v28
	s_waitcnt lgkmcnt(2)
	v_add_f32_e32 v5, v5, v11
	s_waitcnt lgkmcnt(1)
	v_add_f32_e32 v5, v5, v12
	v_ashrrev_i32_e32 v4, 6, v4
	s_waitcnt lgkmcnt(0)
	v_add_f32_e32 v3, v5, v3
	v_and_b32_e32 v5, 3, v4
	v_lshlrev_b32_e32 v4, 1, v4
	v_and_b32_e32 v4, 0x3ffffff8, v4
	v_or3_b32 v2, v5, v4, v2
	v_mul_lo_u32 v2, v2, s10
	v_add3_u32 v2, 0, v2, v6
	v_add_u32_e32 v40, s14, v24
	ds_write_b32 v2, v3 offset:32768
	v_lshlrev_b32_e32 v2, 5, v40
	v_ashrrev_i32_e32 v3, 31, v2
	v_lshl_add_u64 v[42:43], v[2:3], 2, s[2:3]
	s_waitcnt lgkmcnt(0)
	s_barrier
; DI unsigned pk2(float a, float b) { f32x2 v = {a, b}; bf2_t r = __builtin_convertvector(v, bf2_t); return __builtin_bit_cast(unsigned, r); }
; DI float frsq(float x) { return __builtin_amdgcn_rsqf(x); }
; DI void phase_p6(const Params& P, unsigned char* lds) {
;     ...
;             const int rl = t >> 4, cl = (t & 15) * 2; const int srow = 32 * rg + rl, col = 32 * cg + cl;
;             float ss = 0.f;
; #pragma unroll
;             for (int j = 0; j < 8; ++j) { const f32x4 sv = *(const f32x4*)(SSQS + srow * 32 + 4 * j); ss += (sv.x + sv.y) + (sv.z + sv.w); }
;             const float rstd = frsq(ss * (1.f / 1024.f) + EPS);
;             const float u0 = fmaxf(c1[rl * 33 + cl] * rstd, 0.f), u1 = fmaxf(c1[rl * 33 + cl + 1] * rstd, 0.f);
;             __builtin_nontemporal_store(pk2(u0 * u0, u1 * u1), (unsigned*)(U + (size_t)(MPR + srow) * 4096 + col));
;             __syncthreads();
	global_load_dwordx4 v[2:5], v[42:43], off
	global_load_dwordx4 v[6:9], v[42:43], off offset:16
	global_load_dwordx4 v[10:13], v[42:43], off offset:32
	global_load_dwordx4 v[14:17], v[42:43], off offset:48
	global_load_dwordx4 v[20:23], v[42:43], off offset:64
	global_load_dwordx4 v[28:31], v[42:43], off offset:80
	global_load_dwordx4 v[32:35], v[42:43], off offset:96
	global_load_dwordx4 v[36:39], v[42:43], off offset:112
	s_lshl_b32 s14, s13, 5
	s_and_b32 s14, s14, 0xfe0
	v_ashrrev_i32_e32 v41, 31, v40
	s_add_i32 s11, s11, s12
	s_waitcnt vmcnt(7)
	v_mov_b32_e32 v42, v2
	s_waitcnt vmcnt(6)
	v_mov_b32_e32 v43, v6
	v_mov_b32_e32 v6, v3
	v_mov_b32_e32 v2, v4
	v_mov_b32_e32 v3, v8
	v_mov_b32_e32 v8, v5
	s_waitcnt vmcnt(5)
	v_mov_b32_e32 v4, v11
	v_mov_b32_e32 v5, v12
	v_mov_b32_e32 v11, v13
	v_pk_add_f32 v[6:7], v[42:43], v[6:7]
	v_pk_add_f32 v[2:3], v[2:3], v[8:9]
	v_pk_add_f32 v[4:5], v[4:5], v[10:11]
	v_pk_add_f32 v[2:3], v[6:7], v[2:3]
	v_pk_add_f32 v[4:5], v[4:5], v[4:5] op_sel:[0,1] op_sel_hi:[1,0]
	v_add_f32_e32 v2, 0, v2
	s_waitcnt vmcnt(4)
	v_add_f32_e32 v12, v14, v15
	v_add_f32_e32 v14, v16, v17
	s_waitcnt vmcnt(3)
	v_mov_b32_e32 v17, v20
	v_mov_b32_e32 v13, v22
	v_mov_b32_e32 v15, v23
	v_mov_b32_e32 v5, v21
	v_add_f32_e32 v16, v2, v3
	s_waitcnt vmcnt(2)
	v_mov_b32_e32 v22, v29
	v_mov_b32_e32 v23, v30
	v_mov_b32_e32 v29, v31
	v_pk_add_f32 v[8:9], v[12:13], v[14:15]
	v_pk_add_f32 v[2:3], v[16:17], v[4:5]
	v_pk_add_f32 v[10:11], v[22:23], v[28:29]
	v_pk_add_f32 v[2:3], v[2:3], v[8:9]
	v_pk_add_f32 v[6:7], v[10:11], v[10:11] op_sel:[0,1] op_sel_hi:[1,0]
	v_pk_add_f32 v[2:3], v[2:3], v[2:3] op_sel:[0,1] op_sel_hi:[1,0]
	s_waitcnt vmcnt(1)
	v_add_f32_e32 v30, v32, v33
	v_add_f32_e32 v32, v34, v35
	s_waitcnt vmcnt(0)
	v_mov_b32_e32 v31, v38
	v_mov_b32_e32 v33, v39
	v_mov_b32_e32 v7, v37
	v_mov_b32_e32 v3, v36
	v_pk_add_f32 v[2:3], v[2:3], v[6:7]
	v_pk_add_f32 v[4:5], v[30:31], v[32:33]
	s_nop 0
	v_pk_add_f32 v[2:3], v[2:3], v[4:5]
	v_or_b32_e32 v5, s14, v25
	v_add_f32_e32 v2, v2, v3
	v_fmamk_f32 v4, v2, 0x3a800000, v26
	ds_read2_b32 v[2:3], v27 offset1:1
	v_rsq_f32_e32 v4, v4
	v_lshlrev_b32_e32 v18, 1, v5
	v_readlane_b32 s14, v223, 3
	s_add_i32 s13, s13, s14
	s_waitcnt lgkmcnt(0)
	v_mul_f32_e32 v2, v2, v4
	v_mul_f32_e32 v3, v3, v4
	v_max_f32_e32 v2, 0, v2
	v_max_f32_e32 v3, 0, v3
	v_pk_mul_f32 v[2:3], v[2:3], v[2:3]
	s_cmpk_lt_i32 s13, 0x400
	v_cvt_pk_bf16_f32 v4, v2, v3
	v_lshlrev_b64 v[2:3], 13, v[40:41]
	v_lshl_add_u64 v[2:3], s[0:1], 0, v[2:3]
	v_lshl_add_u64 v[2:3], v[2:3], 0, v[18:19]
	v_add_co_u32_e32 v2, vcc, 0x10400000, v2
	v_readlane_b32 s15, v223, 4
	s_nop 0
	v_addc_co_u32_e32 v3, vcc, 0, v3, vcc
	global_store_dword v[2:3], v4, off nt
	s_barrier
	s_cbranch_scc1 .LBB0_1646

; #define MFMA(a, b, c) __builtin_amdgcn_mfma_f32_32x32x16_bf16((a), (b), (c), 0, 0, 0)
; DI int crow(int i, int h) { return (i & 3) + 8 * (i >> 2) + 4 * h; }
; DI int opaque_tid() { int t = threadIdx.x; asm volatile("" : "+v"(t)); return t; }
; DI f32x16 zero16() { f32x16 z; for (int i = 0; i < 16; ++i) z[i] = 0.f; return z; }
; DI void small_tile(const bf16_t* A, size_t lda, int a0, const bf16_t* Bt, size_t ldb, int b0, int K, float* ctile, float* red) {
;     const int t = opaque_tid(), w = t >> 6, lane = t & 63, r = lane & 31, hh = lane >> 5;
;     const int kper = K >> 3;
;     const bf16_t* ap = A + (size_t)(a0 + r) * lda + w * kper + 8 * hh;
;     const bf16_t* bp = Bt + (size_t)(b0 + r) * ldb + w * kper + 8 * hh;
;     f32x16 acc = zero16();
; #pragma unroll 4
;     for (int k = 0; k < kper; k += 16) acc = MFMA(*(const bf16x8*)(ap + k), *(const bf16x8*)(bp + k), acc);
; #pragma unroll
;     for (int i = 0; i < 16; ++i) red[w * 1024 + i * 64 + lane] = acc[i];
;     __syncthreads();
; #pragma unroll
;     for (int q = 0; q < 2; ++q) {
;         const int e = t + 512 * q; float s = 0.f;
; #pragma unroll
;         for (int ww = 0; ww < 8; ++ww) s += red[ww * 1024 + e];
;         const int i = e >> 6, ln = e & 63;
;         ctile[crow(i, ln >> 5) * 33 + (ln & 31)] = s;
;     }
;     __syncthreads();
; }
; DI void phase_p7(const Params& P, unsigned char* lds) {
;     ...
;             small_tile(U, 4096, MPR + 32 * rg, W, 4096, 32 * cg, 4096, c1, red);
;             const int rl = t >> 4, cl = (t & 15) * 2; const int srow = 32 * rg + rl, col = 32 * cg + cl;
;             f32x2* yp = (f32x2*)(P.out + O_YS + (size_t)srow * 1024 + col);
;             f32x2 yv = *yp; yv.x += c1[rl * 33 + cl]; yv.y += c1[rl * 33 + cl + 1]; *yp = yv;
;             __syncthreads();
.LBB0_1730:
	global_load_dwordx4 v[224:227], v[22:23], off offset:-64
	global_load_dwordx4 v[228:231], v[20:21], off offset:-64
	global_load_dwordx4 v[232:235], v[22:23], off offset:-32
	global_load_dwordx4 v[236:239], v[20:21], off offset:-32
	global_load_dwordx4 v[240:243], v[22:23], off
	global_load_dwordx4 v[244:247], v[20:21], off
	global_load_dwordx4 v[248:251], v[22:23], off offset:32
	global_load_dwordx4 v[252:255], v[20:21], off offset:32
	v_lshl_add_u64 v[22:23], v[22:23], 0, s[6:7]
	v_lshl_add_u64 v[20:21], v[20:21], 0, s[6:7]
	s_mov_b32 s12, 0
.Lst7_loop:
	global_load_dwordx4 v[52:55], v[22:23], off offset:-64
	global_load_dwordx4 v[56:59], v[20:21], off offset:-64
	global_load_dwordx4 v[60:63], v[22:23], off offset:-32
	global_load_dwordx4 v[64:67], v[20:21], off offset:-32
	global_load_dwordx4 v[68:71], v[22:23], off
	global_load_dwordx4 v[72:75], v[20:21], off
	global_load_dwordx4 v[76:79], v[22:23], off offset:32
	global_load_dwordx4 v[80:83], v[20:21], off offset:32
	v_lshl_add_u64 v[22:23], v[22:23], 0, s[6:7]
	v_lshl_add_u64 v[20:21], v[20:21], 0, s[6:7]
	s_waitcnt vmcnt(14)
	v_mfma_f32_32x32x16_bf16 v[2:17], v[224:227], v[228:231], v[2:17]
	s_waitcnt vmcnt(12)
	v_mfma_f32_32x32x16_bf16 v[2:17], v[232:235], v[236:239], v[2:17]
	s_waitcnt vmcnt(10)
	v_mfma_f32_32x32x16_bf16 v[2:17], v[240:243], v[244:247], v[2:17]
	s_waitcnt vmcnt(8)
	v_mfma_f32_32x32x16_bf16 v[2:17], v[248:251], v[252:255], v[2:17]
	s_add_i32 s12, s12, 1
	s_cmp_lt_u32 s12, 4
	s_cbranch_scc0 .Lst7_last
	global_load_dwordx4 v[224:227], v[22:23], off offset:-64
	global_load_dwordx4 v[228:231], v[20:21], off offset:-64
	global_load_dwordx4 v[232:235], v[22:23], off offset:-32
	global_load_dwordx4 v[236:239], v[20:21], off offset:-32
	global_load_dwordx4 v[240:243], v[22:23], off
	global_load_dwordx4 v[244:247], v[20:21], off
	global_load_dwordx4 v[248:251], v[22:23], off offset:32
	global_load_dwordx4 v[252:255], v[20:21], off offset:32
	v_lshl_add_u64 v[22:23], v[22:23], 0, s[6:7]
	v_lshl_add_u64 v[20:21], v[20:21], 0, s[6:7]
	s_waitcnt vmcnt(14)
	v_mfma_f32_32x32x16_bf16 v[2:17], v[52:55], v[56:59], v[2:17]
	s_waitcnt vmcnt(12)
	v_mfma_f32_32x32x16_bf16 v[2:17], v[60:63], v[64:67], v[2:17]
	s_waitcnt vmcnt(10)
	v_mfma_f32_32x32x16_bf16 v[2:17], v[68:71], v[72:75], v[2:17]
	s_waitcnt vmcnt(8)
	v_mfma_f32_32x32x16_bf16 v[2:17], v[76:79], v[80:83], v[2:17]
	s_branch .Lst7_loop
.Lst7_last:
	s_waitcnt vmcnt(6)
	v_mfma_f32_32x32x16_bf16 v[2:17], v[52:55], v[56:59], v[2:17]
	s_waitcnt vmcnt(4)
	v_mfma_f32_32x32x16_bf16 v[2:17], v[60:63], v[64:67], v[2:17]
	s_waitcnt vmcnt(2)
	v_mfma_f32_32x32x16_bf16 v[2:17], v[68:71], v[72:75], v[2:17]
	s_waitcnt vmcnt(0)
	v_mfma_f32_32x32x16_bf16 v[2:17], v[76:79], v[80:83], v[2:17]
	s_mov_b32 s12, 0x1f0
	v_and_b32_e32 v18, 63, v27
	v_lshlrev_b32_e32 v20, 12, v29
	v_lshlrev_b32_e32 v18, 2, v18
	v_add3_u32 v18, 0, v20, v18
	s_nop 6
	ds_write2st64_b32 v18, v2, v3 offset1:1
	ds_write2st64_b32 v18, v4, v5 offset0:2 offset1:3
	ds_write2st64_b32 v18, v6, v7 offset0:4 offset1:5
	ds_write2st64_b32 v18, v8, v9 offset0:6 offset1:7
	ds_write2st64_b32 v18, v10, v11 offset0:8 offset1:9
	ds_write2st64_b32 v18, v12, v13 offset0:10 offset1:11
	ds_write2st64_b32 v18, v14, v15 offset0:12 offset1:13
	ds_write2st64_b32 v18, v16, v17 offset0:14 offset1:15
	v_lshl_add_u32 v3, v27, 2, 0
	s_waitcnt lgkmcnt(0)
	s_barrier
	ds_read_b32 v4, v3
	ds_read_b32 v5, v3 offset:4096
	ds_read_b32 v6, v3 offset:8192
	ds_read_b32 v7, v3 offset:12288
	ds_read_b32 v8, v3 offset:16384
	ds_read_b32 v9, v3 offset:20480
	ds_read_b32 v10, v3 offset:24576
	ds_read_b32 v11, v3 offset:28672
	s_waitcnt lgkmcnt(7)
	v_add_f32_e32 v4, 0, v4
	s_waitcnt lgkmcnt(6)
	v_add_f32_e32 v4, v4, v5
	s_waitcnt lgkmcnt(5)
	v_add_f32_e32 v4, v4, v6
	v_lshrrev_b32_e32 v2, 3, v27
	s_waitcnt lgkmcnt(4)
	v_add_f32_e32 v4, v4, v7
	v_lshlrev_b32_e32 v6, 1, v29
	v_and_b32_e32 v2, 4, v2
	s_waitcnt lgkmcnt(3)
	v_add_f32_e32 v4, v4, v8
	v_bfe_u32 v5, v27, 6, 2
	v_and_b32_e32 v6, 0x3ffffff8, v6
	s_waitcnt lgkmcnt(2)
	v_add_f32_e32 v4, v4, v9
	v_or3_b32 v5, v5, v6, v2
	s_waitcnt lgkmcnt(1)
	v_add_f32_e32 v4, v4, v10
	v_mul_lo_u32 v5, v5, s8
	v_lshlrev_b32_e32 v6, 2, v28
	s_waitcnt lgkmcnt(0)
	v_add_f32_e32 v4, v4, v11
	v_add3_u32 v5, 0, v5, v6
	ds_write_b32 v5, v4 offset:32768
	ds_read_b32 v5, v3 offset:2048
	ds_read_b32 v7, v3 offset:6144
	ds_read_b32 v8, v3 offset:10240
	ds_read_b32 v9, v3 offset:14336
	ds_read_b32 v10, v3 offset:18432
	ds_read_b32 v11, v3 offset:22528
	ds_read_b32 v12, v3 offset:26624
	ds_read_b32 v3, v3 offset:30720
	s_waitcnt lgkmcnt(7)
	v_add_f32_e32 v5, 0, v5
	s_waitcnt lgkmcnt(6)
	v_add_f32_e32 v5, v5, v7
	s_waitcnt lgkmcnt(5)
	v_add_f32_e32 v5, v5, v8
	s_waitcnt lgkmcnt(4)
	v_add_f32_e32 v5, v5, v9
	s_waitcnt lgkmcnt(3)
	v_add_f32_e32 v5, v5, v10
	v_add_u32_e32 v4, 0x200, v27
	s_waitcnt lgkmcnt(2)
	v_add_f32_e32 v5, v5, v11
	s_waitcnt lgkmcnt(1)
	v_add_f32_e32 v5, v5, v12
	v_ashrrev_i32_e32 v4, 6, v4
	s_waitcnt lgkmcnt(0)
	v_add_f32_e32 v3, v5, v3
	v_and_b32_e32 v5, 3, v4
	v_lshlrev_b32_e32 v4, 1, v4
	v_and_b32_e32 v4, 0x3ffffff8, v4
	v_or3_b32 v2, v5, v4, v2
	v_mul_lo_u32 v2, v2, s8
	v_add3_u32 v2, 0, v2, v6
	s_lshl_b32 s12, s33, 5
	ds_write_b32 v2, v3 offset:32768
	v_add_u32_e32 v2, s11, v24
	s_and_b32 s12, s12, 0x3e0
	v_ashrrev_i32_e32 v3, 31, v2
	v_or_b32_e32 v4, s12, v25
	v_lshlrev_b64 v[2:3], 12, v[2:3]
	v_lshl_add_u64 v[2:3], s[0:1], 0, v[2:3]
	v_lshlrev_b32_e32 v18, 2, v4
	v_lshl_add_u64 v[2:3], v[2:3], 0, v[18:19]
	s_waitcnt lgkmcnt(0)
	s_barrier
	global_load_dwordx2 v[4:5], v[2:3], off
	ds_read2_b32 v[6:7], v26 offset1:1
	v_readlane_b32 s12, v223, 3
	s_add_i32 s33, s33, s12
	s_add_i32 s9, s9, s10
	s_cmpk_lt_i32 s33, 0x100
	v_readlane_b32 s13, v223, 4
	s_waitcnt vmcnt(0) lgkmcnt(0)
	v_pk_add_f32 v[4:5], v[4:5], v[6:7]
	global_store_dwordx2 v[2:3], v[4:5], off
	s_barrier
	s_cbranch_scc1 .LBB0_1729
